# v33 + GEMM2 mid-loop wait skipped when the start sample of YRDY already showed all 16 units
# speedup vs baseline: 1.0036x; 1.0019x over previous
.LBB0_365:
	s_and_b32 s73, s72, 31
	s_and_saveexec_b64 s[16:17], s[38:39]
	s_cbranch_execz .LBB0_392
	s_lshl_b32 s0, s73, 2
	v_readlane_b32 s18, v254, 28
	v_readlane_b32 s19, v254, 29
	s_or_b32 s18, s0, s18
	s_ashr_i32 s19, s18, 31
	s_lshl_b64 s[18:19], s[18:19], 2
	v_readlane_b32 s26, v252, 29
	v_readlane_b32 s27, v252, 30
	s_add_u32 s18, s26, s18
	s_addc_u32 s19, s27, s19
	v_mov_b32_e32 v176, s18
	v_mov_b32_e32 v177, s19
	global_load_dword v0, v81, s[18:19] offset:4 sc1
	global_load_dword v192, v81, s[18:19] sc1
	s_waitcnt vmcnt(0)
	v_cmp_lt_u32_e32 vcc, 9, v0
	s_cbranch_vccnz .LBB0_379
	s_mov_b32 s0, 1
	s_branch .LBB0_369

.LBB0_393:
	s_and_b32 s0, s28, 1
	s_xor_b32 s29, s0, 1
	s_mul_i32 s29, s29, 0xc000
	s_add_i32 s34, s52, s29
	v_lshl_add_u64 v[94:95], v[92:93], 0, s[26:27]
	s_mul_i32 s0, s0, 0xc000
	s_add_i32 s29, s50, s29
	s_mov_b32 m0, s34
	v_lshl_add_u64 v[96:97], v[88:89], 0, s[26:27]
	s_add_i32 s0, s0, 0
	global_load_lds_dwordx4 v[94:95], off
	s_add_i32 m0, s29, 0x4000
	v_lshl_add_u64 v[98:99], v[86:87], 0, s[26:27]
	v_add_u32_e32 v80, s0, v153
	v_add_u32_e32 v139, s0, v154
	global_load_lds_dwordx4 v[96:97], off
	s_add_i32 m0, s29, 0x4400
	v_add_u32_e32 v146, v80, v151
	v_add_u32_e32 v110, v139, v151
	global_load_lds_dwordx4 v[98:99], off
	ds_read_b128 v[94:97], v146
	ds_read_b128 v[98:101], v110 offset:16384
	ds_read_b128 v[102:105], v110 offset:18432
	ds_read_b128 v[106:109], v110 offset:20480
	ds_read_b128 v[110:113], v110 offset:22528
	s_waitcnt lgkmcnt(0)
	v_mfma_f32_16x16x32_bf16 v[76:79], v[94:97], v[98:101], v[76:79]
	v_lshl_add_u64 v[140:141], v[90:91], 0, s[26:27]
	s_add_i32 s0, s29, 0x4800
	s_add_i32 m0, s34, 0x400
	v_mfma_f32_16x16x32_bf16 v[72:75], v[94:97], v[102:105], v[72:75]
	v_lshl_add_u64 v[142:143], v[82:83], 0, s[26:27]
	s_addk_i32 s29, 0x4c00
	v_lshl_add_u64 v[144:145], v[84:85], 0, s[26:27]
	v_mfma_f32_16x16x32_bf16 v[68:71], v[94:97], v[106:109], v[68:71]
	v_add_u32_e32 v80, v80, v152
	v_add_u32_e32 v139, v139, v152
	s_add_i32 s28, s28, 1
	v_mfma_f32_16x16x32_bf16 v[64:67], v[94:97], v[110:113], v[64:67]
	ds_read_b128 v[94:97], v146 offset:2048
	s_add_u32 s26, s26, 0x80
	s_addc_u32 s27, s27, 0
	s_waitcnt lgkmcnt(0)
	v_mfma_f32_16x16x32_bf16 v[60:63], v[94:97], v[98:101], v[60:63]
	s_cmpk_eq_i32 s26, 0x780
	v_mfma_f32_16x16x32_bf16 v[56:59], v[94:97], v[102:105], v[56:59]
	v_mfma_f32_16x16x32_bf16 v[52:55], v[94:97], v[106:109], v[52:55]
	v_mfma_f32_16x16x32_bf16 v[48:51], v[94:97], v[110:113], v[48:51]
	ds_read_b128 v[94:97], v146 offset:4096
	s_waitcnt lgkmcnt(0)
	v_mfma_f32_16x16x32_bf16 v[44:47], v[94:97], v[98:101], v[44:47]
	v_mfma_f32_16x16x32_bf16 v[40:43], v[94:97], v[102:105], v[40:43]
	v_mfma_f32_16x16x32_bf16 v[32:35], v[94:97], v[106:109], v[32:35]
	v_mfma_f32_16x16x32_bf16 v[24:27], v[94:97], v[110:113], v[24:27]
	ds_read_b128 v[94:97], v146 offset:6144
	global_load_lds_dwordx4 v[140:141], off
	s_mov_b32 m0, s0
	s_waitcnt lgkmcnt(0)
	v_mfma_f32_16x16x32_bf16 v[20:23], v[94:97], v[98:101], v[20:23]
	global_load_lds_dwordx4 v[142:143], off
	s_mov_b32 m0, s29
	v_mfma_f32_16x16x32_bf16 v[16:19], v[94:97], v[102:105], v[16:19]
	global_load_lds_dwordx4 v[144:145], off
	ds_read_b128 v[98:101], v80
	v_mfma_f32_16x16x32_bf16 v[36:39], v[94:97], v[106:109], v[36:39]
	ds_read_b128 v[102:105], v139 offset:18432
	ds_read_b128 v[106:109], v139 offset:20480
	v_mfma_f32_16x16x32_bf16 v[28:31], v[94:97], v[110:113], v[28:31]
	ds_read_b128 v[94:97], v139 offset:16384
	ds_read_b128 v[110:113], v139 offset:22528
	s_waitcnt lgkmcnt(0)
	v_mfma_f32_16x16x32_bf16 v[76:79], v[98:101], v[94:97], v[76:79]
	v_mfma_f32_16x16x32_bf16 v[72:75], v[98:101], v[102:105], v[72:75]
	v_mfma_f32_16x16x32_bf16 v[68:71], v[98:101], v[106:109], v[68:71]
	v_mfma_f32_16x16x32_bf16 v[64:67], v[98:101], v[110:113], v[64:67]
	ds_read_b128 v[98:101], v80 offset:2048
	s_waitcnt lgkmcnt(0)
	v_mfma_f32_16x16x32_bf16 v[60:63], v[98:101], v[94:97], v[60:63]
	v_mfma_f32_16x16x32_bf16 v[56:59], v[98:101], v[102:105], v[56:59]
	v_mfma_f32_16x16x32_bf16 v[52:55], v[98:101], v[106:109], v[52:55]
	v_mfma_f32_16x16x32_bf16 v[48:51], v[98:101], v[110:113], v[48:51]
	ds_read_b128 v[98:101], v80 offset:4096
	s_waitcnt lgkmcnt(0)
	v_mfma_f32_16x16x32_bf16 v[44:47], v[98:101], v[94:97], v[44:47]
	v_mfma_f32_16x16x32_bf16 v[40:43], v[98:101], v[102:105], v[40:43]
	v_mfma_f32_16x16x32_bf16 v[32:35], v[98:101], v[106:109], v[32:35]
	v_mfma_f32_16x16x32_bf16 v[24:27], v[98:101], v[110:113], v[24:27]
	ds_read_b128 v[98:101], v80 offset:6144
	s_cmpk_lg_i32 s26, 0x480
	s_cbranch_scc1 .Lg2_mid_done
	s_mov_b64 s[100:101], exec
	s_mov_b64 exec, s[38:39]
	s_cbranch_execz .Lg2_mid_rest
	v_mov_b32_e32 v190, 0
	v_cmp_lt_u32_e32 vcc, 15, v192
	s_cbranch_vccnz .Lg2_mid_rest
